# out-proj (residual add) GEMM epilogue: src loads issued in two batches of 14 into dead MFMA-operand registers
# speedup vs baseline: 1.0203x; 1.0033x over previous
;     DI void operator()(const f32x4 (&acc)[2][2][4][2], const Unit& u, int wr, int wc, int fr, int fq) const {
;         const int row0 = u.pm * BM + wr * 64 + fr, col0 = u.pn * BM + wc * 32 + 8 * fq;
; #pragma unroll
;         for (int ai = 0; ai < 2; ++ai)
; #pragma unroll
;             for (int m = 0; m < 4; ++m)
; #pragma unroll
;                 for (int bj = 0; bj < 2; ++bj) f.store8(row0 + ai * HALF + m * 16, col0 + bj * HALF, acc[ai][bj][m][0], acc[ai][bj][m][1]);
;     }
;     DI void store8(int row, int col, f32x4 a, f32x4 b) const {
;         const size_t o = (size_t)(row - rowoff) * 1024 + col;
;         const f32x4 s0 = *(const f32x4*)(src + o), s1 = *(const f32x4*)(src + o + 4);
;         if (!dry) { *(f32x4*)(dst + o) = s0 + a; *(f32x4*)(dst + o + 4) = s1 + b; }
;     }
.LBB0_210:
	v_lshl_add_u32 v144, s38, 8, v146
	v_lshl_or_b32 v142, s39, 8, v148
	v_ashrrev_i32_e32 v145, 31, v144
	v_lshlrev_b64 v[140:141], 10, v[144:145]
	v_ashrrev_i32_e32 v143, 31, v142
	v_lshl_add_u64 v[140:141], v[140:141], 0, v[142:143]
	v_lshlrev_b64 v[140:141], 2, v[140:141]
	v_lshl_add_u64 v[158:159], s[12:13], 0, v[140:141]
	global_load_dwordx4 v[150:153], v[158:159], off offset:16
	global_load_dwordx4 v[154:157], v[158:159], off
	s_mov_b64 s[100:101], 0x0
	v_lshl_add_u64 v[162:163], v[158:159], 0, s[100:101]
	global_load_dwordx4 v[176:179], v[162:163], off offset:528
	global_load_dwordx4 v[180:183], v[162:163], off offset:512
	s_mov_b64 s[100:101], 0x10000
	v_lshl_add_u64 v[162:163], v[158:159], 0, s[100:101]
	global_load_dwordx4 v[190:193], v[162:163], off offset:16
	global_load_dwordx4 v[194:197], v[162:163], off
	global_load_dwordx4 v[198:201], v[162:163], off offset:528
	global_load_dwordx4 v[202:205], v[162:163], off offset:512
	s_mov_b64 s[100:101], 0x20000
	v_lshl_add_u64 v[162:163], v[158:159], 0, s[100:101]
	global_load_dwordx4 v[206:209], v[162:163], off offset:16
	global_load_dwordx4 v[210:213], v[162:163], off
	global_load_dwordx4 v[214:217], v[162:163], off offset:528
	global_load_dwordx4 v[218:221], v[162:163], off offset:512
	s_mov_b64 s[100:101], 0x30000
	v_lshl_add_u64 v[162:163], v[158:159], 0, s[100:101]
	global_load_dwordx4 v[222:225], v[162:163], off offset:16
	global_load_dwordx4 v[226:229], v[162:163], off
	global_load_dwordx4 v[248:251], v[162:163], off offset:528
	global_load_dwordx4 v[252:255], v[162:163], off offset:512
	s_mov_b64 s[38:39], 0x80000
	s_andn2_b64 vcc, exec, s[4:5]
	s_waitcnt vmcnt(0)
	v_pk_add_f32 v[124:125], v[124:125], v[152:153]
	v_pk_add_f32 v[128:129], v[128:129], v[156:157]
	v_pk_add_f32 v[126:127], v[126:127], v[154:155]
	v_lshl_add_u64 v[154:155], s[56:57], 0, v[140:141]
	v_pk_add_f32 v[122:123], v[122:123], v[150:151]
	global_store_dwordx4 v[154:155], v[126:129], off
	global_store_dwordx4 v[154:155], v[122:125], off offset:16
	s_nop 0
	s_nop 0
	s_nop 0
	v_pk_add_f32 v[116:117], v[116:117], v[178:179]
	v_pk_add_f32 v[114:115], v[114:115], v[176:177]
	global_store_dwordx4 v[154:155], v[114:117], off offset:528
	v_pk_add_f32 v[120:121], v[120:121], v[182:183]
	v_pk_add_f32 v[118:119], v[118:119], v[180:181]
	v_or_b32_e32 v114, 16, v144
	v_ashrrev_i32_e32 v115, 31, v114
	v_lshlrev_b64 v[114:115], 10, v[114:115]
	v_lshl_add_u64 v[114:115], v[114:115], 0, v[142:143]
	v_lshlrev_b64 v[122:123], 2, v[114:115]
	global_store_dwordx4 v[154:155], v[118:121], off offset:512
	v_lshl_add_u64 v[124:125], s[12:13], 0, v[122:123]
	s_nop 0
	s_nop 0
	v_pk_add_f32 v[108:109], v[108:109], v[192:193]
	v_pk_add_f32 v[112:113], v[112:113], v[196:197]
	v_pk_add_f32 v[110:111], v[110:111], v[194:195]
	v_lshl_add_u64 v[118:119], s[56:57], 0, v[122:123]
	v_pk_add_f32 v[106:107], v[106:107], v[190:191]
	global_store_dwordx4 v[118:119], v[110:113], off
	global_store_dwordx4 v[118:119], v[106:109], off offset:16
	s_nop 0
	s_nop 0
	s_nop 0
	v_pk_add_f32 v[100:101], v[100:101], v[200:201]
	v_pk_add_f32 v[98:99], v[98:99], v[198:199]
	global_store_dwordx4 v[118:119], v[98:101], off offset:528
	v_pk_add_f32 v[104:105], v[104:105], v[204:205]
	v_pk_add_f32 v[102:103], v[102:103], v[202:203]
	v_or_b32_e32 v98, 32, v144
	v_ashrrev_i32_e32 v99, 31, v98
	v_lshlrev_b64 v[98:99], 10, v[98:99]
	v_lshl_add_u64 v[98:99], v[98:99], 0, v[142:143]
	v_lshlrev_b64 v[106:107], 2, v[98:99]
	global_store_dwordx4 v[118:119], v[102:105], off offset:512
	v_lshl_add_u64 v[108:109], s[12:13], 0, v[106:107]
	s_nop 0
	s_nop 0
	v_pk_add_f32 v[92:93], v[92:93], v[208:209]
	v_pk_add_f32 v[96:97], v[96:97], v[212:213]
	v_pk_add_f32 v[94:95], v[94:95], v[210:211]
	v_lshl_add_u64 v[102:103], s[56:57], 0, v[106:107]
	v_pk_add_f32 v[90:91], v[90:91], v[206:207]
	global_store_dwordx4 v[102:103], v[94:97], off
	global_store_dwordx4 v[102:103], v[90:93], off offset:16
	s_nop 0
	s_nop 0
	s_nop 0
	v_pk_add_f32 v[84:85], v[84:85], v[216:217]
	v_pk_add_f32 v[82:83], v[82:83], v[214:215]
	global_store_dwordx4 v[102:103], v[82:85], off offset:528
	v_pk_add_f32 v[88:89], v[88:89], v[220:221]
	v_pk_add_f32 v[86:87], v[86:87], v[218:219]
	v_or_b32_e32 v82, 48, v144
	v_ashrrev_i32_e32 v83, 31, v82
	v_lshlrev_b64 v[82:83], 10, v[82:83]
	v_lshl_add_u64 v[82:83], v[82:83], 0, v[142:143]
	v_lshlrev_b64 v[90:91], 2, v[82:83]
	global_store_dwordx4 v[102:103], v[86:89], off offset:512
	v_lshl_add_u64 v[92:93], s[12:13], 0, v[90:91]
	s_nop 0
	s_nop 0
	v_pk_add_f32 v[76:77], v[76:77], v[224:225]
	v_pk_add_f32 v[80:81], v[80:81], v[228:229]
	v_pk_add_f32 v[78:79], v[78:79], v[226:227]
	v_lshl_add_u64 v[86:87], s[56:57], 0, v[90:91]
	v_pk_add_f32 v[74:75], v[74:75], v[222:223]
	global_store_dwordx4 v[86:87], v[78:81], off
	global_store_dwordx4 v[86:87], v[74:77], off offset:16
	s_nop 0
	s_nop 0
	s_nop 0
	v_pk_add_f32 v[68:69], v[68:69], v[250:251]
	v_pk_add_f32 v[72:73], v[72:73], v[254:255]
	v_pk_add_f32 v[70:71], v[70:71], v[252:253]
	v_pk_add_f32 v[66:67], v[66:67], v[248:249]
	v_lshl_add_u64 v[74:75], v[140:141], 0, s[38:39]
	global_store_dwordx4 v[86:87], v[70:73], off offset:512
	global_store_dwordx4 v[86:87], v[66:69], off offset:528
	v_lshl_add_u64 v[76:77], s[12:13], 0, v[74:75]
	global_load_dwordx4 v[66:69], v[76:77], off offset:16
	global_load_dwordx4 v[70:73], v[76:77], off
	s_mov_b64 s[100:101], 0x80000
	v_lshl_add_u64 v[162:163], v[158:159], 0, s[100:101]
	global_load_dwordx4 v[176:179], v[162:163], off offset:528
	global_load_dwordx4 v[180:183], v[162:163], off offset:512
	s_mov_b64 s[100:101], 0x90000
	v_lshl_add_u64 v[162:163], v[158:159], 0, s[100:101]
	global_load_dwordx4 v[190:193], v[162:163], off offset:16
	global_load_dwordx4 v[194:197], v[162:163], off
	global_load_dwordx4 v[198:201], v[162:163], off offset:528
	global_load_dwordx4 v[202:205], v[162:163], off offset:512
	s_mov_b64 s[100:101], 0xa0000
	v_lshl_add_u64 v[162:163], v[158:159], 0, s[100:101]
	global_load_dwordx4 v[206:209], v[162:163], off offset:16
	global_load_dwordx4 v[210:213], v[162:163], off
	global_load_dwordx4 v[214:217], v[162:163], off offset:528
	global_load_dwordx4 v[218:221], v[162:163], off offset:512
	s_mov_b64 s[100:101], 0xb0000
	v_lshl_add_u64 v[162:163], v[158:159], 0, s[100:101]
	global_load_dwordx4 v[222:225], v[162:163], off offset:16
	global_load_dwordx4 v[226:229], v[162:163], off
	global_load_dwordx4 v[248:251], v[162:163], off offset:528
	global_load_dwordx4 v[252:255], v[162:163], off offset:512
	s_mov_b64 s[38:39], 0x90000
	s_waitcnt vmcnt(0)
;     DI void operator()(const f32x4 (&acc)[2][2][4][2], const Unit& u, int wr, int wc, int fr, int fq) const {
;         const int row0 = u.pm * BM + wr * 64 + fr, col0 = u.pn * BM + wc * 32 + 8 * fq;
; #pragma unroll
;         for (int ai = 0; ai < 2; ++ai)
; #pragma unroll
;             for (int m = 0; m < 4; ++m)
; #pragma unroll
;                 for (int bj = 0; bj < 2; ++bj) f.store8(row0 + ai * HALF + m * 16, col0 + bj * HALF, acc[ai][bj][m][0], acc[ai][bj][m][1]);
;     }
;     DI void store8(int row, int col, f32x4 a, f32x4 b) const {
;         const size_t o = (size_t)(row - rowoff) * 1024 + col;
;         const f32x4 s0 = *(const f32x4*)(src + o), s1 = *(const f32x4*)(src + o + 4);
;         if (!dry) { *(f32x4*)(dst + o) = s0 + a; *(f32x4*)(dst + o + 4) = s1 + b; }
;     }
	v_pk_add_f32 v[60:61], v[60:61], v[68:69]
	s_waitcnt vmcnt(0)
	v_pk_add_f32 v[64:65], v[64:65], v[72:73]
	v_pk_add_f32 v[62:63], v[62:63], v[70:71]
	v_lshl_add_u64 v[70:71], s[56:57], 0, v[74:75]
	v_pk_add_f32 v[58:59], v[58:59], v[66:67]
	global_store_dwordx4 v[70:71], v[62:65], off
	global_store_dwordx4 v[70:71], v[58:61], off offset:16
	s_nop 0
	s_nop 0
	s_nop 0
	v_pk_add_f32 v[52:53], v[52:53], v[178:179]
	v_pk_add_f32 v[56:57], v[56:57], v[182:183]
	v_pk_add_f32 v[54:55], v[54:55], v[180:181]
	v_pk_add_f32 v[50:51], v[50:51], v[176:177]
	v_lshl_add_u64 v[58:59], v[140:141], 0, s[38:39]
	global_store_dwordx4 v[70:71], v[54:57], off offset:512
	global_store_dwordx4 v[70:71], v[50:53], off offset:528
	v_lshl_add_u64 v[60:61], s[12:13], 0, v[58:59]
	s_nop 0
	s_nop 0
	s_mov_b64 s[38:39], 0xa0000
	v_pk_add_f32 v[44:45], v[44:45], v[192:193]
	v_pk_add_f32 v[48:49], v[48:49], v[196:197]
	v_pk_add_f32 v[46:47], v[46:47], v[194:195]
	v_lshl_add_u64 v[54:55], s[56:57], 0, v[58:59]
	v_pk_add_f32 v[42:43], v[42:43], v[190:191]
	global_store_dwordx4 v[54:55], v[46:49], off
	global_store_dwordx4 v[54:55], v[42:45], off offset:16
	s_nop 0
	s_nop 0
	s_nop 0
	v_pk_add_f32 v[36:37], v[36:37], v[200:201]
	v_pk_add_f32 v[40:41], v[40:41], v[204:205]
	v_pk_add_f32 v[38:39], v[38:39], v[202:203]
	v_pk_add_f32 v[34:35], v[34:35], v[198:199]
	v_lshl_add_u64 v[42:43], v[140:141], 0, s[38:39]
	global_store_dwordx4 v[54:55], v[38:41], off offset:512
	global_store_dwordx4 v[54:55], v[34:37], off offset:528
	v_lshl_add_u64 v[44:45], s[12:13], 0, v[42:43]
	s_nop 0
	s_nop 0
	s_mov_b64 s[38:39], 0xb0000
	v_pk_add_f32 v[28:29], v[28:29], v[208:209]
	v_pk_add_f32 v[32:33], v[32:33], v[212:213]
	v_pk_add_f32 v[30:31], v[30:31], v[210:211]
	v_lshl_add_u64 v[38:39], s[56:57], 0, v[42:43]
	v_pk_add_f32 v[26:27], v[26:27], v[206:207]
	global_store_dwordx4 v[38:39], v[30:33], off
	global_store_dwordx4 v[38:39], v[26:29], off offset:16
	s_nop 0
	s_nop 0
	s_nop 0
	v_pk_add_f32 v[20:21], v[20:21], v[216:217]
	v_pk_add_f32 v[24:25], v[24:25], v[220:221]
	v_pk_add_f32 v[22:23], v[22:23], v[218:219]
	v_pk_add_f32 v[18:19], v[18:19], v[214:215]
	v_lshl_add_u64 v[26:27], v[140:141], 0, s[38:39]
	global_store_dwordx4 v[38:39], v[22:25], off offset:512
	global_store_dwordx4 v[38:39], v[18:21], off offset:528
	v_lshl_add_u64 v[28:29], s[12:13], 0, v[26:27]
	s_nop 0
	s_nop 0
	s_mov_b64 s[38:39], -1
	v_pk_add_f32 v[12:13], v[12:13], v[224:225]
	v_pk_add_f32 v[16:17], v[16:17], v[228:229]
	v_pk_add_f32 v[14:15], v[14:15], v[226:227]
	v_lshl_add_u64 v[22:23], s[56:57], 0, v[26:27]
	v_pk_add_f32 v[10:11], v[10:11], v[222:223]
	global_store_dwordx4 v[22:23], v[14:17], off
	global_store_dwordx4 v[22:23], v[10:13], off offset:16
	s_nop 0
	s_nop 0
	s_nop 0
	v_pk_add_f32 v[4:5], v[4:5], v[250:251]
	v_pk_add_f32 v[8:9], v[8:9], v[254:255]
	v_pk_add_f32 v[6:7], v[6:7], v[252:253]
	v_pk_add_f32 v[2:3], v[2:3], v[248:249]
	global_store_dwordx4 v[22:23], v[6:9], off offset:512
	global_store_dwordx4 v[22:23], v[2:5], off offset:528
	s_cbranch_vccnz .LBB0_199
	s_andn2_b64 vcc, exec, s[10:11]
	s_cbranch_vccnz .LBB0_198
	s_barrier
	s_branch .LBB0_198
